# K-loop: first iteration after an epilogue runs without LDS-DMA waits (next tile's 8 pieces pre-issued before the epilogue stores) so the store drain overlaps ~3 phases of MFMA work
# speedup vs baseline: 1.0021x; 1.0021x over previous
.LBB0_901:
	s_mov_b32 s101, 0
	v_readlane_b32 s48, v254, 46
	v_readlane_b32 s50, v254, 44
	v_readlane_b32 s56, v254, 40
	v_readlane_b32 s52, v254, 38
	v_readlane_b32 s38, v254, 36
	v_readlane_b32 s24, v254, 34
	v_readlane_b32 s58, v254, 20
	s_mov_b64 s[54:55], 0
	s_cmp_lg_u32 s93, 1
	v_readlane_b32 s49, v254, 47
	v_readlane_b32 s51, v254, 45
	v_readlane_b32 s57, v254, 41
	v_readlane_b32 s53, v254, 39
	v_readlane_b32 s39, v254, 37
	v_readlane_b32 s25, v254, 35
	v_readlane_b32 s59, v254, 21
	v_readlane_b32 s96, v254, 5
	s_cbranch_scc1 .LBB0_903
	s_waitcnt vmcnt(0)
	v_readlane_b32 s58, v254, 48
	v_readlane_b32 s48, v254, 29
	v_readlane_b32 s50, v254, 42
	v_readlane_b32 s56, v254, 31
	v_readlane_b32 s59, v254, 49
	v_readlane_b32 s36, v254, 27
	v_readlane_b32 s10, v253, 51
	s_movk_i32 s94, 0x100
	s_mov_b64 s[52:53], 0
	v_readlane_b32 s49, v254, 30
	v_readlane_b32 s51, v254, 43
	v_readlane_b32 s57, v254, 32
	s_mov_b64 s[38:39], s[12:13]
	s_mov_b64 s[54:55], s[58:59]
	s_mov_b64 s[24:25], 0
	v_readlane_b32 s96, v254, 33
	v_readlane_b32 s37, v254, 28
	v_readlane_b32 s11, v253, 52
	s_barrier

.LBB0_919:
	s_add_i32 s42, s20, 2
	s_cmp_eq_u32 s42, 2
	s_cselect_b32 s100, s101, 0
	s_add_u32 s24, s18, 0x80
	s_addc_u32 s21, s19, 0
	s_add_i32 s43, 0, 0x10000
	v_add_u32_e32 v0, s43, v211
	s_waitcnt lgkmcnt(0)
	ds_read_b128 v[130:133], v0
	ds_read_b128 v[134:137], v0 offset:1024
	ds_read_b128 v[138:141], v0 offset:2048
	ds_read_b128 v[142:145], v0 offset:3072
	s_cmp_eq_u32 s66, s20
	s_cselect_b32 s20, s74, s24
	s_cselect_b32 s21, s75, s21
	s_cselect_b32 s25, s77, s39
	s_cselect_b32 s24, s76, s38
	s_add_i32 s44, 0, 0x14000
	v_add_u32_e32 v0, s44, v211
	v_lshl_add_u64 v[198:199], s[18:19], 0, v[184:185]
	s_add_i32 m0, s31, 0xc000
	ds_read_b128 v[232:235], v0
	ds_read_b128 v[236:239], v0 offset:1024
	ds_read_b128 v[240:243], v0 offset:2048
	ds_read_b128 v[244:247], v0 offset:3072
	s_cmp_lg_u32 s100, 0
	s_cbranch_scc1 .Lk_skipst_m
	global_load_lds_dwordx4 v[198:199], off
	v_lshl_add_u64 v[198:199], s[18:19], 0, v[182:183]
	s_add_i32 m0, s31, 0xe000
	s_nop 0
	global_load_lds_dwordx4 v[198:199], off
.Lk_skipst_m:
	ds_read_b128 v[146:149], v212
	ds_read_b128 v[150:153], v212 offset:1024
	ds_read_b128 v[154:157], v212 offset:2048
	ds_read_b128 v[158:161], v212 offset:3072
	ds_read_b128 v[186:189], v212 offset:4096
	ds_read_b128 v[190:193], v212 offset:5120
	s_waitcnt lgkmcnt(12)
	ds_read_b128 v[194:197], v212 offset:6144
	ds_read_b128 v[214:217], v212 offset:7168
	s_cmp_lg_u32 s100, 0
	s_cbranch_scc1 .Lk_w1_m
	s_waitcnt vmcnt(8)
.Lk_w1_m:
	s_waitcnt lgkmcnt(0)
	s_barrier
	s_setprio 1
	v_mfma_f32_16x16x32_bf16 v[126:129], v[130:133], v[146:149], v[126:129]
	v_mfma_f32_16x16x32_bf16 v[122:125], v[138:141], v[146:149], v[122:125]
	v_mfma_f32_16x16x32_bf16 v[110:113], v[130:133], v[154:157], v[110:113]
	v_mfma_f32_16x16x32_bf16 v[106:109], v[138:141], v[154:157], v[106:109]
	v_mfma_f32_16x16x32_bf16 v[94:97], v[130:133], v[186:189], v[94:97]
	v_mfma_f32_16x16x32_bf16 v[90:93], v[138:141], v[186:189], v[90:93]
	v_mfma_f32_16x16x32_bf16 v[78:81], v[130:133], v[194:197], v[78:81]
	v_mfma_f32_16x16x32_bf16 v[74:77], v[138:141], v[194:197], v[74:77]
	v_mfma_f32_16x16x32_bf16 v[126:129], v[134:137], v[150:153], v[126:129]
	v_mfma_f32_16x16x32_bf16 v[122:125], v[142:145], v[150:153], v[122:125]
	v_mfma_f32_16x16x32_bf16 v[110:113], v[134:137], v[158:161], v[110:113]
	v_mfma_f32_16x16x32_bf16 v[106:109], v[142:145], v[158:161], v[106:109]
	v_mfma_f32_16x16x32_bf16 v[94:97], v[134:137], v[190:193], v[94:97]
	v_mfma_f32_16x16x32_bf16 v[90:93], v[142:145], v[190:193], v[90:93]
	v_mfma_f32_16x16x32_bf16 v[78:81], v[134:137], v[214:217], v[78:81]
	v_mfma_f32_16x16x32_bf16 v[74:77], v[142:145], v[214:217], v[74:77]
	v_mfma_f32_16x16x32_bf16 v[118:121], v[232:235], v[146:149], v[118:121]
	v_mfma_f32_16x16x32_bf16 v[114:117], v[240:243], v[146:149], v[114:117]
	v_mfma_f32_16x16x32_bf16 v[102:105], v[232:235], v[154:157], v[102:105]
	v_mfma_f32_16x16x32_bf16 v[98:101], v[240:243], v[154:157], v[98:101]
	v_mfma_f32_16x16x32_bf16 v[86:89], v[232:235], v[186:189], v[86:89]
	v_mfma_f32_16x16x32_bf16 v[82:85], v[240:243], v[186:189], v[82:85]
	v_mfma_f32_16x16x32_bf16 v[70:73], v[232:235], v[194:197], v[70:73]
	v_mfma_f32_16x16x32_bf16 v[66:69], v[240:243], v[194:197], v[66:69]
	v_mfma_f32_16x16x32_bf16 v[118:121], v[236:239], v[150:153], v[118:121]
	v_mfma_f32_16x16x32_bf16 v[114:117], v[244:247], v[150:153], v[114:117]
	v_mfma_f32_16x16x32_bf16 v[102:105], v[236:239], v[158:161], v[102:105]
	v_mfma_f32_16x16x32_bf16 v[98:101], v[244:247], v[158:161], v[98:101]
	v_mfma_f32_16x16x32_bf16 v[86:89], v[236:239], v[190:193], v[86:89]
	v_mfma_f32_16x16x32_bf16 v[82:85], v[244:247], v[190:193], v[82:85]
	v_mfma_f32_16x16x32_bf16 v[70:73], v[236:239], v[214:217], v[70:73]
	v_mfma_f32_16x16x32_bf16 v[66:69], v[244:247], v[214:217], v[66:69]
	s_barrier
	s_setprio 0
	ds_read_b128 v[146:149], v212 offset:16384
	ds_read_b128 v[150:153], v212 offset:17408
	ds_read_b128 v[154:157], v212 offset:18432
	ds_read_b128 v[158:161], v212 offset:19456
	ds_read_b128 v[186:189], v212 offset:20480
	ds_read_b128 v[190:193], v212 offset:21504
	ds_read_b128 v[194:197], v212 offset:22528
	ds_read_b128 v[214:217], v212 offset:23552
	s_add_i32 s43, s43, s30
	v_lshl_add_u64 v[198:199], s[24:25], 0, v[170:171]
	s_mov_b32 m0, s43
	v_lshl_add_u64 v[218:219], s[24:25], 0, v[174:175]
	global_load_lds_dwordx4 v[198:199], off
	s_add_i32 m0, s43, 0x2000
	s_nop 0
	global_load_lds_dwordx4 v[218:219], off
	s_mov_b32 m0, s31
	v_lshl_add_u64 v[248:249], s[20:21], 0, v[168:169]
	v_lshl_add_u64 v[250:251], s[20:21], 0, v[172:173]
	global_load_lds_dwordx4 v[248:249], off
	s_mov_b32 m0, s95
	s_nop 0
	global_load_lds_dwordx4 v[250:251], off
	s_add_u32 s24, s24, s60
	s_addc_u32 s25, s25, 0
	s_add_i32 s43, s44, s30
	v_lshl_add_u64 v[226:227], s[24:25], 0, v[170:171]
	s_mov_b32 m0, s43
	v_lshl_add_u64 v[228:229], s[24:25], 0, v[174:175]
	global_load_lds_dwordx4 v[226:227], off
	s_add_i32 m0, s43, 0x2000
	s_nop 0
	global_load_lds_dwordx4 v[228:229], off
	s_cmp_lg_u32 s100, 0
	s_cbranch_scc1 .Lk_w2_m
	s_waitcnt vmcnt(8)
.Lk_w2_m:
	s_waitcnt lgkmcnt(0)
	s_barrier
	s_setprio 1
	v_mfma_f32_16x16x32_bf16 v[62:65], v[130:133], v[146:149], v[62:65]
	v_mfma_f32_16x16x32_bf16 v[58:61], v[138:141], v[146:149], v[58:61]
	v_mfma_f32_16x16x32_bf16 v[46:49], v[130:133], v[154:157], v[46:49]
	v_mfma_f32_16x16x32_bf16 v[42:45], v[138:141], v[154:157], v[42:45]
	v_mfma_f32_16x16x32_bf16 v[30:33], v[130:133], v[186:189], v[30:33]
	v_mfma_f32_16x16x32_bf16 v[26:29], v[138:141], v[186:189], v[26:29]
	v_mfma_f32_16x16x32_bf16 v[14:17], v[130:133], v[194:197], v[14:17]
	v_mfma_f32_16x16x32_bf16 v[10:13], v[138:141], v[194:197], v[10:13]
	v_mfma_f32_16x16x32_bf16 v[62:65], v[134:137], v[150:153], v[62:65]
	v_mfma_f32_16x16x32_bf16 v[58:61], v[142:145], v[150:153], v[58:61]
	v_mfma_f32_16x16x32_bf16 v[46:49], v[134:137], v[158:161], v[46:49]
	v_mfma_f32_16x16x32_bf16 v[42:45], v[142:145], v[158:161], v[42:45]
	v_mfma_f32_16x16x32_bf16 v[30:33], v[134:137], v[190:193], v[30:33]
	v_mfma_f32_16x16x32_bf16 v[26:29], v[142:145], v[190:193], v[26:29]
	v_mfma_f32_16x16x32_bf16 v[14:17], v[134:137], v[214:217], v[14:17]
	v_mfma_f32_16x16x32_bf16 v[10:13], v[142:145], v[214:217], v[10:13]
	v_mfma_f32_16x16x32_bf16 v[54:57], v[232:235], v[146:149], v[54:57]
	v_mfma_f32_16x16x32_bf16 v[50:53], v[240:243], v[146:149], v[50:53]
	v_mfma_f32_16x16x32_bf16 v[38:41], v[232:235], v[154:157], v[38:41]
	v_mfma_f32_16x16x32_bf16 v[34:37], v[240:243], v[154:157], v[34:37]
	v_mfma_f32_16x16x32_bf16 v[22:25], v[232:235], v[186:189], v[22:25]
	v_mfma_f32_16x16x32_bf16 v[18:21], v[240:243], v[186:189], v[18:21]
	v_mfma_f32_16x16x32_bf16 v[6:9], v[232:235], v[194:197], v[6:9]
	v_mfma_f32_16x16x32_bf16 v[2:5], v[240:243], v[194:197], v[2:5]
	v_mfma_f32_16x16x32_bf16 v[54:57], v[236:239], v[150:153], v[54:57]
	v_mfma_f32_16x16x32_bf16 v[50:53], v[244:247], v[150:153], v[50:53]
	v_mfma_f32_16x16x32_bf16 v[38:41], v[236:239], v[158:161], v[38:41]
	v_mfma_f32_16x16x32_bf16 v[34:37], v[244:247], v[158:161], v[34:37]
	v_mfma_f32_16x16x32_bf16 v[22:25], v[236:239], v[190:193], v[22:25]
	v_mfma_f32_16x16x32_bf16 v[18:21], v[244:247], v[190:193], v[18:21]
	v_mfma_f32_16x16x32_bf16 v[6:9], v[236:239], v[214:217], v[6:9]
	v_mfma_f32_16x16x32_bf16 v[2:5], v[244:247], v[214:217], v[2:5]
	s_barrier
	s_setprio 0
	s_add_u32 s20, s20, s60
	s_addc_u32 s21, s21, 0
	s_mov_b32 m0, s8
	v_lshl_add_u64 v[232:233], s[20:21], 0, v[168:169]
	s_add_i32 s24, 0, 0x18000
	v_add_u32_e32 v0, s24, v211
	global_load_lds_dwordx4 v[232:233], off
	v_lshl_add_u64 v[232:233], s[20:21], 0, v[172:173]
	s_mov_b32 m0, s9
	s_nop 0
	global_load_lds_dwordx4 v[232:233], off
	ds_read_b128 v[130:133], v0
	ds_read_b128 v[134:137], v0 offset:1024
	ds_read_b128 v[138:141], v0 offset:2048
	ds_read_b128 v[142:145], v0 offset:3072
	s_add_i32 s20, 0, 0x1c000
	s_add_i32 s21, s24, s30
	v_add_u32_e32 v0, s20, v211
	ds_read_b128 v[232:235], v0
	ds_read_b128 v[236:239], v0 offset:1024
	ds_read_b128 v[240:243], v0 offset:2048
	ds_read_b128 v[244:247], v0 offset:3072
	ds_read_b128 v[146:149], v212 offset:32768
	ds_read_b128 v[150:153], v212 offset:33792
	ds_read_b128 v[154:157], v212 offset:34816
	ds_read_b128 v[158:161], v212 offset:35840
	ds_read_b128 v[186:189], v212 offset:36864
	ds_read_b128 v[190:193], v212 offset:37888
	s_waitcnt lgkmcnt(12)
	ds_read_b128 v[194:197], v212 offset:38912
	ds_read_b128 v[214:217], v212 offset:39936
	s_cmp_lg_u32 s100, 0
	s_cbranch_scc1 .Lk_w3_m
	s_waitcnt vmcnt(8)
.Lk_w3_m:
	s_waitcnt lgkmcnt(0)
	s_barrier
	s_setprio 1
	v_mfma_f32_16x16x32_bf16 v[126:129], v[130:133], v[146:149], v[126:129]
	v_mfma_f32_16x16x32_bf16 v[122:125], v[138:141], v[146:149], v[122:125]
	v_mfma_f32_16x16x32_bf16 v[110:113], v[130:133], v[154:157], v[110:113]
	v_mfma_f32_16x16x32_bf16 v[106:109], v[138:141], v[154:157], v[106:109]
	v_mfma_f32_16x16x32_bf16 v[94:97], v[130:133], v[186:189], v[94:97]
	v_mfma_f32_16x16x32_bf16 v[90:93], v[138:141], v[186:189], v[90:93]
	v_mfma_f32_16x16x32_bf16 v[78:81], v[130:133], v[194:197], v[78:81]
	v_mfma_f32_16x16x32_bf16 v[74:77], v[138:141], v[194:197], v[74:77]
	v_mfma_f32_16x16x32_bf16 v[126:129], v[134:137], v[150:153], v[126:129]
	v_mfma_f32_16x16x32_bf16 v[122:125], v[142:145], v[150:153], v[122:125]
	v_mfma_f32_16x16x32_bf16 v[110:113], v[134:137], v[158:161], v[110:113]
	v_mfma_f32_16x16x32_bf16 v[106:109], v[142:145], v[158:161], v[106:109]
	v_mfma_f32_16x16x32_bf16 v[94:97], v[134:137], v[190:193], v[94:97]
	v_mfma_f32_16x16x32_bf16 v[90:93], v[142:145], v[190:193], v[90:93]
	v_mfma_f32_16x16x32_bf16 v[78:81], v[134:137], v[214:217], v[78:81]
	v_mfma_f32_16x16x32_bf16 v[74:77], v[142:145], v[214:217], v[74:77]
	v_mfma_f32_16x16x32_bf16 v[118:121], v[232:235], v[146:149], v[118:121]
	v_mfma_f32_16x16x32_bf16 v[114:117], v[240:243], v[146:149], v[114:117]
	v_mfma_f32_16x16x32_bf16 v[102:105], v[232:235], v[154:157], v[102:105]
	v_mfma_f32_16x16x32_bf16 v[98:101], v[240:243], v[154:157], v[98:101]
	v_mfma_f32_16x16x32_bf16 v[86:89], v[232:235], v[186:189], v[86:89]
	v_mfma_f32_16x16x32_bf16 v[82:85], v[240:243], v[186:189], v[82:85]
	v_mfma_f32_16x16x32_bf16 v[70:73], v[232:235], v[194:197], v[70:73]
	v_mfma_f32_16x16x32_bf16 v[66:69], v[240:243], v[194:197], v[66:69]
	v_mfma_f32_16x16x32_bf16 v[118:121], v[236:239], v[150:153], v[118:121]
	v_mfma_f32_16x16x32_bf16 v[114:117], v[244:247], v[150:153], v[114:117]
	v_mfma_f32_16x16x32_bf16 v[102:105], v[236:239], v[158:161], v[102:105]
	v_mfma_f32_16x16x32_bf16 v[98:101], v[244:247], v[158:161], v[98:101]
	v_mfma_f32_16x16x32_bf16 v[86:89], v[236:239], v[190:193], v[86:89]
	v_mfma_f32_16x16x32_bf16 v[82:85], v[244:247], v[190:193], v[82:85]
	v_mfma_f32_16x16x32_bf16 v[70:73], v[236:239], v[214:217], v[70:73]
	v_mfma_f32_16x16x32_bf16 v[66:69], v[244:247], v[214:217], v[66:69]
	s_barrier
	s_setprio 0
	ds_read_b128 v[146:149], v212 offset:49152
	ds_read_b128 v[150:153], v212 offset:50176
	ds_read_b128 v[154:157], v212 offset:51200
	ds_read_b128 v[158:161], v212 offset:52224
	ds_read_b128 v[186:189], v212 offset:53248
	ds_read_b128 v[190:193], v212 offset:54272
	ds_read_b128 v[194:197], v212 offset:55296
	ds_read_b128 v[214:217], v212 offset:56320
	v_lshl_add_u64 v[198:199], v[198:199], 0, s[16:17]
	s_mov_b32 m0, s21
	v_lshl_add_u64 v[218:219], v[218:219], 0, s[16:17]
	global_load_lds_dwordx4 v[198:199], off
	s_add_i32 m0, s21, 0x2000
	s_nop 0
	global_load_lds_dwordx4 v[218:219], off
	s_mov_b32 m0, s97
	v_lshl_add_u64 v[248:249], v[248:249], 0, s[16:17]
	v_lshl_add_u64 v[250:251], v[250:251], 0, s[16:17]
	global_load_lds_dwordx4 v[248:249], off
	s_mov_b32 m0, s90
	s_nop 0
	global_load_lds_dwordx4 v[250:251], off
	s_add_i32 s20, s20, s30
	v_lshl_add_u64 v[226:227], v[226:227], 0, s[16:17]
	s_mov_b32 m0, s20
	v_lshl_add_u64 v[228:229], v[228:229], 0, s[16:17]
	global_load_lds_dwordx4 v[226:227], off
	s_add_i32 m0, s20, 0x2000
	s_nop 0
	global_load_lds_dwordx4 v[228:229], off
	s_waitcnt vmcnt(8) lgkmcnt(0)
	s_barrier
	s_setprio 1
	v_mfma_f32_16x16x32_bf16 v[62:65], v[130:133], v[146:149], v[62:65]
	v_mfma_f32_16x16x32_bf16 v[58:61], v[138:141], v[146:149], v[58:61]
	v_mfma_f32_16x16x32_bf16 v[46:49], v[130:133], v[154:157], v[46:49]
	v_mfma_f32_16x16x32_bf16 v[42:45], v[138:141], v[154:157], v[42:45]
	v_mfma_f32_16x16x32_bf16 v[30:33], v[130:133], v[186:189], v[30:33]
	v_mfma_f32_16x16x32_bf16 v[26:29], v[138:141], v[186:189], v[26:29]
	v_mfma_f32_16x16x32_bf16 v[14:17], v[130:133], v[194:197], v[14:17]
	v_mfma_f32_16x16x32_bf16 v[10:13], v[138:141], v[194:197], v[10:13]
	v_mfma_f32_16x16x32_bf16 v[62:65], v[134:137], v[150:153], v[62:65]
	v_mfma_f32_16x16x32_bf16 v[58:61], v[142:145], v[150:153], v[58:61]
	v_mfma_f32_16x16x32_bf16 v[46:49], v[134:137], v[158:161], v[46:49]
	v_mfma_f32_16x16x32_bf16 v[42:45], v[142:145], v[158:161], v[42:45]
	v_mfma_f32_16x16x32_bf16 v[30:33], v[134:137], v[190:193], v[30:33]
	v_mfma_f32_16x16x32_bf16 v[26:29], v[142:145], v[190:193], v[26:29]
	v_mfma_f32_16x16x32_bf16 v[14:17], v[134:137], v[214:217], v[14:17]
	v_mfma_f32_16x16x32_bf16 v[10:13], v[142:145], v[214:217], v[10:13]
	v_mfma_f32_16x16x32_bf16 v[54:57], v[232:235], v[146:149], v[54:57]
	v_mfma_f32_16x16x32_bf16 v[50:53], v[240:243], v[146:149], v[50:53]
	v_mfma_f32_16x16x32_bf16 v[38:41], v[232:235], v[154:157], v[38:41]
	v_mfma_f32_16x16x32_bf16 v[34:37], v[240:243], v[154:157], v[34:37]
	v_mfma_f32_16x16x32_bf16 v[22:25], v[232:235], v[186:189], v[22:25]
	v_mfma_f32_16x16x32_bf16 v[18:21], v[240:243], v[186:189], v[18:21]
	v_mfma_f32_16x16x32_bf16 v[6:9], v[232:235], v[194:197], v[6:9]
	v_mfma_f32_16x16x32_bf16 v[2:5], v[240:243], v[194:197], v[2:5]
	v_mfma_f32_16x16x32_bf16 v[54:57], v[236:239], v[150:153], v[54:57]
	v_mfma_f32_16x16x32_bf16 v[50:53], v[244:247], v[150:153], v[50:53]
	v_mfma_f32_16x16x32_bf16 v[38:41], v[236:239], v[158:161], v[38:41]
	v_mfma_f32_16x16x32_bf16 v[34:37], v[244:247], v[158:161], v[34:37]
	v_mfma_f32_16x16x32_bf16 v[22:25], v[236:239], v[190:193], v[22:25]
	v_mfma_f32_16x16x32_bf16 v[18:21], v[244:247], v[190:193], v[18:21]
	v_mfma_f32_16x16x32_bf16 v[6:9], v[236:239], v[214:217], v[6:9]
	v_mfma_f32_16x16x32_bf16 v[2:5], v[244:247], v[214:217], v[2:5]
	s_add_u32 s38, s38, 0x100
	s_addc_u32 s39, s39, 0
	s_add_u32 s18, s18, 0x100
	s_addc_u32 s19, s19, 0
	s_cmp_ge_u32 s42, s91
	s_mov_b32 s20, s42
	s_barrier
	s_setprio 0
	s_cbranch_scc0 .LBB0_919
	s_branch .Lkloop_done
.Lkloop_narrow:
	s_add_i32 s42, s20, 2
	s_cmp_eq_u32 s42, 2
	s_cselect_b32 s100, s101, 0
	s_add_u32 s24, s18, 0x80
	s_addc_u32 s21, s19, 0
	s_add_i32 s43, 0, 0x10000
	v_add_u32_e32 v0, s43, v211
	s_waitcnt lgkmcnt(0)
	ds_read_b128 v[130:133], v0
	ds_read_b128 v[134:137], v0 offset:1024
	ds_read_b128 v[138:141], v0 offset:2048
	ds_read_b128 v[142:145], v0 offset:3072
	s_cmp_eq_u32 s66, s20
	s_cselect_b32 s20, s74, s24
	s_cselect_b32 s21, s75, s21
	s_cselect_b32 s25, s77, s39
	s_cselect_b32 s24, s76, s38
	s_add_i32 s44, 0, 0x14000
	v_add_u32_e32 v0, s44, v211
	v_lshl_add_u64 v[198:199], s[18:19], 0, v[184:185]
	s_add_i32 m0, s31, 0xc000
	s_cmp_lg_u32 s100, 0
	s_cbranch_scc1 .Lk_skipst_n
	global_load_lds_dwordx4 v[198:199], off
	v_lshl_add_u64 v[198:199], s[18:19], 0, v[182:183]
	s_add_i32 m0, s31, 0xe000
	s_nop 0
	global_load_lds_dwordx4 v[198:199], off

.Lk_w1_n:
	s_waitcnt lgkmcnt(0)
	s_barrier
	s_setprio 1
	v_mfma_f32_16x16x32_bf16 v[126:129], v[130:133], v[146:149], v[126:129]
	v_mfma_f32_16x16x32_bf16 v[122:125], v[138:141], v[146:149], v[122:125]
	v_mfma_f32_16x16x32_bf16 v[110:113], v[130:133], v[154:157], v[110:113]
	v_mfma_f32_16x16x32_bf16 v[106:109], v[138:141], v[154:157], v[106:109]
	v_mfma_f32_16x16x32_bf16 v[94:97], v[130:133], v[186:189], v[94:97]
	v_mfma_f32_16x16x32_bf16 v[90:93], v[138:141], v[186:189], v[90:93]
	v_mfma_f32_16x16x32_bf16 v[78:81], v[130:133], v[194:197], v[78:81]
	v_mfma_f32_16x16x32_bf16 v[74:77], v[138:141], v[194:197], v[74:77]
	v_mfma_f32_16x16x32_bf16 v[126:129], v[134:137], v[150:153], v[126:129]
	v_mfma_f32_16x16x32_bf16 v[122:125], v[142:145], v[150:153], v[122:125]
	v_mfma_f32_16x16x32_bf16 v[110:113], v[134:137], v[158:161], v[110:113]
	v_mfma_f32_16x16x32_bf16 v[106:109], v[142:145], v[158:161], v[106:109]
	v_mfma_f32_16x16x32_bf16 v[94:97], v[134:137], v[190:193], v[94:97]
	v_mfma_f32_16x16x32_bf16 v[90:93], v[142:145], v[190:193], v[90:93]
	v_mfma_f32_16x16x32_bf16 v[78:81], v[134:137], v[214:217], v[78:81]
	v_mfma_f32_16x16x32_bf16 v[74:77], v[142:145], v[214:217], v[74:77]
	s_barrier
	s_setprio 0
	ds_read_b128 v[146:149], v212 offset:16384
	ds_read_b128 v[150:153], v212 offset:17408
	ds_read_b128 v[154:157], v212 offset:18432
	ds_read_b128 v[158:161], v212 offset:19456
	ds_read_b128 v[186:189], v212 offset:20480
	ds_read_b128 v[190:193], v212 offset:21504
	ds_read_b128 v[194:197], v212 offset:22528
	ds_read_b128 v[214:217], v212 offset:23552
	s_add_i32 s43, s43, s30
	v_lshl_add_u64 v[198:199], s[24:25], 0, v[170:171]
	s_mov_b32 m0, s43
	v_lshl_add_u64 v[218:219], s[24:25], 0, v[174:175]
	global_load_lds_dwordx4 v[198:199], off
	s_add_i32 m0, s43, 0x2000
	s_nop 0
	global_load_lds_dwordx4 v[218:219], off
	s_mov_b32 m0, s31
	v_lshl_add_u64 v[248:249], s[20:21], 0, v[168:169]
	v_lshl_add_u64 v[250:251], s[20:21], 0, v[172:173]
	global_load_lds_dwordx4 v[248:249], off
	s_mov_b32 m0, s95
	s_nop 0
	global_load_lds_dwordx4 v[250:251], off
	s_add_u32 s24, s24, s60
	s_addc_u32 s25, s25, 0
	s_add_i32 s43, s44, s30
	v_lshl_add_u64 v[226:227], s[24:25], 0, v[170:171]
	s_mov_b32 m0, s43
	v_lshl_add_u64 v[228:229], s[24:25], 0, v[174:175]
	global_load_lds_dwordx4 v[226:227], off
	s_add_i32 m0, s43, 0x2000
	s_nop 0
	global_load_lds_dwordx4 v[228:229], off
	s_cmp_lg_u32 s100, 0
	s_cbranch_scc1 .Lk_w2_n
	s_waitcnt vmcnt(8)
.Lk_w2_n:
	s_waitcnt lgkmcnt(0)
	s_barrier
	s_setprio 1
	v_mfma_f32_16x16x32_bf16 v[62:65], v[130:133], v[146:149], v[62:65]
	v_mfma_f32_16x16x32_bf16 v[58:61], v[138:141], v[146:149], v[58:61]
	v_mfma_f32_16x16x32_bf16 v[46:49], v[130:133], v[154:157], v[46:49]
	v_mfma_f32_16x16x32_bf16 v[42:45], v[138:141], v[154:157], v[42:45]
	v_mfma_f32_16x16x32_bf16 v[30:33], v[130:133], v[186:189], v[30:33]
	v_mfma_f32_16x16x32_bf16 v[26:29], v[138:141], v[186:189], v[26:29]
	v_mfma_f32_16x16x32_bf16 v[14:17], v[130:133], v[194:197], v[14:17]
	v_mfma_f32_16x16x32_bf16 v[10:13], v[138:141], v[194:197], v[10:13]
	v_mfma_f32_16x16x32_bf16 v[62:65], v[134:137], v[150:153], v[62:65]
	v_mfma_f32_16x16x32_bf16 v[58:61], v[142:145], v[150:153], v[58:61]
	v_mfma_f32_16x16x32_bf16 v[46:49], v[134:137], v[158:161], v[46:49]
	v_mfma_f32_16x16x32_bf16 v[42:45], v[142:145], v[158:161], v[42:45]
	v_mfma_f32_16x16x32_bf16 v[30:33], v[134:137], v[190:193], v[30:33]
	v_mfma_f32_16x16x32_bf16 v[26:29], v[142:145], v[190:193], v[26:29]
	v_mfma_f32_16x16x32_bf16 v[14:17], v[134:137], v[214:217], v[14:17]
	v_mfma_f32_16x16x32_bf16 v[10:13], v[142:145], v[214:217], v[10:13]
	s_barrier
	s_setprio 0
	s_add_u32 s20, s20, s60
	s_addc_u32 s21, s21, 0
	s_mov_b32 m0, s8
	v_lshl_add_u64 v[232:233], s[20:21], 0, v[168:169]
	s_add_i32 s24, 0, 0x18000
	v_add_u32_e32 v0, s24, v211
	global_load_lds_dwordx4 v[232:233], off
	v_lshl_add_u64 v[232:233], s[20:21], 0, v[172:173]
	s_mov_b32 m0, s9
	s_nop 0
	global_load_lds_dwordx4 v[232:233], off
	ds_read_b128 v[130:133], v0
	ds_read_b128 v[134:137], v0 offset:1024
	ds_read_b128 v[138:141], v0 offset:2048
	ds_read_b128 v[142:145], v0 offset:3072
	s_add_i32 s20, 0, 0x1c000
	s_add_i32 s21, s24, s30
	v_add_u32_e32 v0, s20, v211
	ds_read_b128 v[146:149], v212 offset:32768
	ds_read_b128 v[150:153], v212 offset:33792
	ds_read_b128 v[154:157], v212 offset:34816
	ds_read_b128 v[158:161], v212 offset:35840
	ds_read_b128 v[186:189], v212 offset:36864
	ds_read_b128 v[190:193], v212 offset:37888
	s_waitcnt lgkmcnt(12)
	ds_read_b128 v[194:197], v212 offset:38912
	ds_read_b128 v[214:217], v212 offset:39936
	s_cmp_lg_u32 s100, 0
	s_cbranch_scc1 .Lk_w3_n
	s_waitcnt vmcnt(8)
.Lk_w3_n:
	s_waitcnt lgkmcnt(0)
	s_barrier
	s_setprio 1
	v_mfma_f32_16x16x32_bf16 v[126:129], v[130:133], v[146:149], v[126:129]
	v_mfma_f32_16x16x32_bf16 v[122:125], v[138:141], v[146:149], v[122:125]
	v_mfma_f32_16x16x32_bf16 v[110:113], v[130:133], v[154:157], v[110:113]
	v_mfma_f32_16x16x32_bf16 v[106:109], v[138:141], v[154:157], v[106:109]
	v_mfma_f32_16x16x32_bf16 v[94:97], v[130:133], v[186:189], v[94:97]
	v_mfma_f32_16x16x32_bf16 v[90:93], v[138:141], v[186:189], v[90:93]
	v_mfma_f32_16x16x32_bf16 v[78:81], v[130:133], v[194:197], v[78:81]
	v_mfma_f32_16x16x32_bf16 v[74:77], v[138:141], v[194:197], v[74:77]
	v_mfma_f32_16x16x32_bf16 v[126:129], v[134:137], v[150:153], v[126:129]
	v_mfma_f32_16x16x32_bf16 v[122:125], v[142:145], v[150:153], v[122:125]
	v_mfma_f32_16x16x32_bf16 v[110:113], v[134:137], v[158:161], v[110:113]
	v_mfma_f32_16x16x32_bf16 v[106:109], v[142:145], v[158:161], v[106:109]
	v_mfma_f32_16x16x32_bf16 v[94:97], v[134:137], v[190:193], v[94:97]
	v_mfma_f32_16x16x32_bf16 v[90:93], v[142:145], v[190:193], v[90:93]
	v_mfma_f32_16x16x32_bf16 v[78:81], v[134:137], v[214:217], v[78:81]
	v_mfma_f32_16x16x32_bf16 v[74:77], v[142:145], v[214:217], v[74:77]
	s_barrier
	s_setprio 0
	ds_read_b128 v[146:149], v212 offset:49152
	ds_read_b128 v[150:153], v212 offset:50176
	ds_read_b128 v[154:157], v212 offset:51200
	ds_read_b128 v[158:161], v212 offset:52224
	ds_read_b128 v[186:189], v212 offset:53248
	ds_read_b128 v[190:193], v212 offset:54272
	ds_read_b128 v[194:197], v212 offset:55296
	ds_read_b128 v[214:217], v212 offset:56320
	v_lshl_add_u64 v[198:199], v[198:199], 0, s[16:17]
	s_mov_b32 m0, s21
	v_lshl_add_u64 v[218:219], v[218:219], 0, s[16:17]
	global_load_lds_dwordx4 v[198:199], off
	s_add_i32 m0, s21, 0x2000
	s_nop 0
	global_load_lds_dwordx4 v[218:219], off
	s_mov_b32 m0, s97
	v_lshl_add_u64 v[248:249], v[248:249], 0, s[16:17]
	v_lshl_add_u64 v[250:251], v[250:251], 0, s[16:17]
	global_load_lds_dwordx4 v[248:249], off
	s_mov_b32 m0, s90
	s_nop 0
	global_load_lds_dwordx4 v[250:251], off
	s_add_i32 s20, s20, s30
	v_lshl_add_u64 v[226:227], v[226:227], 0, s[16:17]
	s_mov_b32 m0, s20
	v_lshl_add_u64 v[228:229], v[228:229], 0, s[16:17]
	global_load_lds_dwordx4 v[226:227], off
	s_add_i32 m0, s20, 0x2000
	s_nop 0
	global_load_lds_dwordx4 v[228:229], off
	s_waitcnt vmcnt(8) lgkmcnt(0)
	s_barrier
	s_setprio 1
	v_mfma_f32_16x16x32_bf16 v[62:65], v[130:133], v[146:149], v[62:65]
	v_mfma_f32_16x16x32_bf16 v[58:61], v[138:141], v[146:149], v[58:61]
	v_mfma_f32_16x16x32_bf16 v[46:49], v[130:133], v[154:157], v[46:49]
	v_mfma_f32_16x16x32_bf16 v[42:45], v[138:141], v[154:157], v[42:45]
	v_mfma_f32_16x16x32_bf16 v[30:33], v[130:133], v[186:189], v[30:33]
	v_mfma_f32_16x16x32_bf16 v[26:29], v[138:141], v[186:189], v[26:29]
	v_mfma_f32_16x16x32_bf16 v[14:17], v[130:133], v[194:197], v[14:17]
	v_mfma_f32_16x16x32_bf16 v[10:13], v[138:141], v[194:197], v[10:13]
	v_mfma_f32_16x16x32_bf16 v[62:65], v[134:137], v[150:153], v[62:65]
	v_mfma_f32_16x16x32_bf16 v[58:61], v[142:145], v[150:153], v[58:61]
	v_mfma_f32_16x16x32_bf16 v[46:49], v[134:137], v[158:161], v[46:49]
	v_mfma_f32_16x16x32_bf16 v[42:45], v[142:145], v[158:161], v[42:45]
	v_mfma_f32_16x16x32_bf16 v[30:33], v[134:137], v[190:193], v[30:33]
	v_mfma_f32_16x16x32_bf16 v[26:29], v[142:145], v[190:193], v[26:29]
	v_mfma_f32_16x16x32_bf16 v[14:17], v[134:137], v[214:217], v[14:17]
	v_mfma_f32_16x16x32_bf16 v[10:13], v[142:145], v[214:217], v[10:13]
	s_add_u32 s38, s38, 0x100
	s_addc_u32 s39, s39, 0
	s_add_u32 s18, s18, 0x100
	s_addc_u32 s19, s19, 0
	s_cmp_ge_u32 s42, s91
	s_mov_b32 s20, s42
	s_barrier
	s_setprio 0
	s_cbranch_scc0 .Lkloop_narrow
.Lkloop_done:
	s_add_u32 s18, s74, 0x80
	s_addc_u32 s19, s75, 0
	v_lshl_add_u64 v[198:199], s[18:19], 0, v[184:185]
	s_add_i32 m0, s31, 0xc000
	s_nop 0
	global_load_lds_dwordx4 v[198:199], off
	v_lshl_add_u64 v[198:199], s[18:19], 0, v[182:183]
	s_add_i32 m0, s31, 0xe000
	s_nop 0
	global_load_lds_dwordx4 v[198:199], off
	s_mov_b32 s101, 1
	s_cmp_eq_u32 s96, 1
	s_cbranch_scc0 .Lk_novlw
	s_waitcnt vmcnt(0)
